# v117 + constant DMA destinations per parity copy and static alternation: each copy has its own short tile head and hands over to the other copy (copy 0 falls through into copy 1)
# baseline (speedup 1.0000x reference)
; #define ATT_LAS __attribute__((address_space(3)))
; #define ATT_STAGE(t, buf) do { _Pragma("unroll") for (int i_ = 0; i_ < 2; ++i_) { \
;         glds16(Kt + (size_t)(t) * 131072, ksrc[i_], (unsigned)__builtin_amdgcn_readfirstlane(ldsb + KBUF + (buf) * 16384 + (w * 2 + i_) * 1024)); \
;         glds16(Vt + (size_t)(t) * 131072, vsrc[i_], (unsigned)__builtin_amdgcn_readfirstlane(ldsb + VBUF + (buf) * 16384 + (w * 2 + i_) * 1024)); } } while (0)
; __device__ __forceinline__ void attn_unit(ATT_LAS unsigned char* lds, const bf16_t* Qg, const bf16_t* Kg, const bf16_t* Vg, bf16_t* Og, int b, int head, int qb, float lam, const float* subg) {
;     ...
;     for (int t = 0; t < NT; ++t) {
;         const int buf = t & 1;
;         if (t + 1 < NT) ATT_STAGE(t + 1, buf ^ 1);
;         const int kvrel = 64 * t - q0 - 32 * wq;
;         if (kvrel <= 31) {
;             const ATT_LAS unsigned char* kb = lds + KBUF + buf * 16384;
;             const ATT_LAS unsigned char* vb = lds + VBUF + buf * 16384;
;             tile_body(kvrel + 63 > 0, kb, vb, qbase, kaddr, vaddr, O1, O2, m1, m2, l1, l2, kvrel, r, h, wsf);
.LBB0_291:
	s_cmp_gt_i32 s80, 31
	s_cbranch_scc1 .Ldma_skip
	s_lshl_b32 s4, s4, 14
	s_add_i32 s81, s4, 0
	s_cmp_eq_u32 s81, 0
	s_cbranch_scc0 .Lbody_p1
	s_branch .Lbody_p0
.Lhead_p0:
	s_add_i32 s79, s79, 1
	s_add_i32 m0, s77, 0x4000
	s_cmp_ge_u32 s79, s76
	s_cbranch_scc1 .Lq_prefetch_p0
	global_load_lds_dwordx4 v198, s[92:93]
.Ltile_p0:
	s_cmp_gt_i32 s80, 31
	s_cbranch_scc1 .Ldma_skip
	s_mov_b32 s81, 0x0
.Lbody_p0:
	ds_read_b128 v[2:5], v203
	ds_read_b128 v[6:9], v217
	ds_read_b128 v[10:13], v204
	ds_read_b128 v[146:149], v219
	ds_read_b128 v[150:153], v205
	ds_read_b128 v[154:157], v221
	ds_read_b128 v[158:161], v206
	ds_read_b128 v[162:165], v223
	s_cmpk_gt_i32 s80, 0xffc1
	s_cselect_b64 s[36:37], -1, 0
	s_cmpk_lt_i32 s80, 0xffc2
	s_waitcnt lgkmcnt(4)
	v_mfma_f32_32x32x16_bf16 v[170:185], v[2:5], v[6:9], 0
	v_mfma_f32_32x32x16_bf16 v[170:185], v[10:13], v[146:149], v[170:185]
	s_waitcnt lgkmcnt(0)
	v_mfma_f32_32x32x16_bf16 v[170:185], v[150:153], v[154:157], v[170:185]
	v_mfma_f32_32x32x16_bf16 v[170:185], v[158:161], v[162:165], v[170:185]
	s_cbranch_scc0 .Lhead_mask_p0
.LBB0_296_p0:
	s_add_i32 m0, s77, 0xc000
	s_cmp_ge_u32 s79, s76
	s_cbranch_scc1 .Ldma_s1_p0
	global_load_lds_dwordx4 v199, s[94:95]

; #define ATT_STAGE(t, buf) do { _Pragma("unroll") for (int i_ = 0; i_ < 2; ++i_) { \
;         glds16(Kt + (size_t)(t) * 131072, ksrc[i_], (unsigned)__builtin_amdgcn_readfirstlane(ldsb + KBUF + (buf) * 16384 + (w * 2 + i_) * 1024)); \
;         glds16(Vt + (size_t)(t) * 131072, vsrc[i_], (unsigned)__builtin_amdgcn_readfirstlane(ldsb + VBUF + (buf) * 16384 + (w * 2 + i_) * 1024)); } } while (0)
; __device__ __forceinline__ void attn_unit(ATT_LAS unsigned char* lds, const bf16_t* Qg, const bf16_t* Kg, const bf16_t* Vg, bf16_t* Og, int b, int head, int qb, float lam, const float* subg) {
;     ...
;         if (t + 1 < NT) ATT_STAGE(t + 1, buf ^ 1);
.Lns_311_p0:
	s_add_i32 m0, s50, 0x4000
	s_cmp_ge_u32 s79, s76
	s_cbranch_scc1 .Ldma_ns2_p0
	global_load_lds_dwordx4 v200, s[92:93]

; #define ATT_STAGE(t, buf) do { _Pragma("unroll") for (int i_ = 0; i_ < 2; ++i_) { \
;         glds16(Kt + (size_t)(t) * 131072, ksrc[i_], (unsigned)__builtin_amdgcn_readfirstlane(ldsb + KBUF + (buf) * 16384 + (w * 2 + i_) * 1024)); \
;         glds16(Vt + (size_t)(t) * 131072, vsrc[i_], (unsigned)__builtin_amdgcn_readfirstlane(ldsb + VBUF + (buf) * 16384 + (w * 2 + i_) * 1024)); } } while (0)
; __device__ __forceinline__ void attn_unit(ATT_LAS unsigned char* lds, const bf16_t* Qg, const bf16_t* Kg, const bf16_t* Vg, bf16_t* Og, int b, int head, int qb, float lam, const float* subg) {
;     ...
;         if (t + 1 < NT) ATT_STAGE(t + 1, buf ^ 1);
.Lns_326_p0:
	s_add_i32 m0, s50, 0xc000
	s_cmp_ge_u32 s79, s76
	s_cbranch_scc1 .Ldma_ns3_p0
	global_load_lds_dwordx4 v201, s[94:95]

; template <bool HAS_PV, bool HAS_QK, bool C1> ...
;     s16x4 vlo[2], vhi[2]; bf16x8 ka, qa;
;     if (HAS_PV) {
; #pragma unroll
;         for (int u = 0; u < 2; ++u) { vlo[u] = vtr(vb + vaddr[0] + u * 512); vhi[u] = vtr(vb + vaddr[1] + u * 512); } }
;     if (HAS_QK) { const int ad = C1 ? sub1(kaddr[0]) : kaddr[0]; ka = *(const ATT_LAS bf16x8*)(kb + ad); qa = *(const ATT_LAS bf16x8*)(qb_ + ad);
; #pragma unroll
;         for (int i = 0; i < 16; ++i) Snext[i] = 0.f; }
;     float sa = 0.f, sb = 0.f;
; #pragma unroll
;     for (int g = 0; g < 4; ++g) {
;         s16x4 nlo[2], nhi[2]; bf16x8 nk, nq;
;         if (g < 3) {
;             if (HAS_PV) {
; #pragma unroll
;                 for (int u = 0; u < 2; ++u) { const int off = (2 * ((g + 1) & 1) + u) * 512 + ((g + 1) >> 1) * 4096; nlo[u] = vtr(vb + vaddr[0] + off); nhi[u] = vtr(vb + vaddr[1] + off); } }
;             if (HAS_QK) { const int ad = C1 ? sub1(kaddr[g + 1]) : kaddr[g + 1]; nk = *(const ATT_LAS bf16x8*)(kb + ad); nq = *(const ATT_LAS bf16x8*)(qb_ + ad); }
;         }
;         if (HAS_PV) { const bf16x8 pa = __builtin_bit_cast(bf16x8, pkin[g >> 1]);
; #pragma unroll
;             for (int u = 0; u < 2; ++u) { const bf16x8 vf = __builtin_shufflevector(vlo[u], vhi[u], 0, 1, 2, 3, 4, 5, 6, 7); Opv[2 * (g & 1) + u] = ATT_MFMA(pa, vf, Opv[2 * (g & 1) + u]); } }
;         if (HAS_QK) Snext = ATT_MFMA(ka, qa, Snext);
; #pragma unroll
;         for (int e = 4 * g; e < 4 * g + 4; e += 2) { Scur[e] = __builtin_amdgcn_exp2f(Scur[e] - m); Scur[e + 1] = __builtin_amdgcn_exp2f(Scur[e + 1] - m); sa += Scur[e]; sb += Scur[e + 1]; }
;         if (g & 1) pkout[g >> 1] = (u32x4){cvtpk(Scur[4 * g - 4], Scur[4 * g - 3]), cvtpk(Scur[4 * g - 2], Scur[4 * g - 1]), cvtpk(Scur[4 * g], Scur[4 * g + 1]), cvtpk(Scur[4 * g + 2], Scur[4 * g + 3])};
;         if (g < 3) {
;             if (HAS_PV) {
; #pragma unroll
;                 for (int u = 0; u < 2; ++u) { vlo[u] = nlo[u]; vhi[u] = nhi[u]; } }
;             if (HAS_QK) { ka = nk; qa = nq; }
;         }
;         __builtin_amdgcn_sched_barrier(0);
;     }
;     l += sa + sb;
;     return sa + sb;
; }
; __device__ __forceinline__ void pv_issue(f32x16 (&O)[4], const u32x4 (&pk)[2], const ATT_LAS unsigned char* vb, const int (&vaddr)[2]) {
; #pragma unroll
;     for (int s_ = 0; s_ < 2; ++s_) { const bf16x8 pa = __builtin_bit_cast(bf16x8, pk[s_]);
; #pragma unroll
.Lns_341_p0:
	ds_read_b64_tr_b16 v[8:9], v213 offset:43008
	ds_read_b64_tr_b16 v[6:7], v207 offset:40960
	ds_read_b64_tr_b16 v[146:147], v207 offset:41472
	ds_read_b64_tr_b16 v[150:151], v207 offset:41984
	ds_read_b64_tr_b16 v[154:155], v207 offset:42496
	ds_read_b64_tr_b16 v[148:149], v213 offset:43520
	ds_read_b64_tr_b16 v[152:153], v213 offset:44032
	ds_read_b64_tr_b16 v[156:157], v213 offset:44544
	s_waitcnt lgkmcnt(1)
	v_mfma_f32_32x32x16_bf16 v[34:49], v[2:5], v[6:9], v[34:49]
	v_exp_f32_e32 v15, v162
	v_exp_f32_e32 v14, v163
	v_exp_f32_e32 v163, v164
	v_mfma_f32_32x32x16_bf16 v[50:65], v[2:5], v[146:149], v[50:65]
	v_exp_f32_e32 v162, v165
	v_mfma_f32_32x32x16_bf16 v[66:81], v[2:5], v[150:153], v[66:81]
	ds_read_b64_tr_b16 v[146:147], v207 offset:45056
	ds_read_b64_tr_b16 v[148:149], v213 offset:47104
	ds_read_b64_tr_b16 v[160:161], v213 offset:47616
	ds_read_b64_tr_b16 v[158:159], v207 offset:45568
	v_exp_f32_e32 v165, v166
	v_exp_f32_e32 v164, v167
	v_exp_f32_e32 v167, v168
	s_waitcnt lgkmcnt(2)
	v_mfma_f32_32x32x16_bf16 v[82:97], v[2:5], v[154:157], v[82:97]
	v_exp_f32_e32 v166, v169
	v_cvt_pk_bf16_f32 v6, v15, v14
	v_cvt_pk_bf16_f32 v7, v163, v162
	v_cvt_pk_bf16_f32 v8, v165, v164
	v_cvt_pk_bf16_f32 v9, v167, v166
	v_mfma_f32_32x32x16_bf16 v[34:49], v[10:13], v[146:149], v[34:49]
	ds_read_b64_tr_b16 v[2:3], v207 offset:46080
	ds_read_b64_tr_b16 v[4:5], v213 offset:48128
	ds_read_b64_tr_b16 v[152:153], v213 offset:48640
	ds_read_b64_tr_b16 v[150:151], v207 offset:46592
	v_exp_f32_e32 v147, v170
	v_exp_f32_e32 v146, v171
	v_exp_f32_e32 v149, v172
	s_waitcnt lgkmcnt(0)
	v_mfma_f32_32x32x16_bf16 v[50:65], v[10:13], v[158:161], v[50:65]
	v_exp_f32_e32 v148, v173
	v_mfma_f32_32x32x16_bf16 v[66:81], v[10:13], v[2:5], v[66:81]
	v_exp_f32_e32 v155, v174
	v_exp_f32_e32 v154, v175
	v_exp_f32_e32 v157, v176
	v_mfma_f32_32x32x16_bf16 v[82:97], v[10:13], v[150:153], v[82:97]
	v_add_f32_e64 v10, v162, v14
	v_add_f32_e64 v11, v163, v15
	v_exp_f32_e32 v156, v177
	v_add_f32_e32 v10, v164, v10
	v_add_f32_e32 v11, v165, v11
	v_cvt_pk_bf16_f32 v2, v147, v146
	v_cvt_pk_bf16_f32 v3, v149, v148
	v_cvt_pk_bf16_f32 v4, v155, v154
	v_cvt_pk_bf16_f32 v5, v157, v156
	v_add_f32_e32 v10, v166, v10
	v_add_f32_e32 v11, v167, v11
	v_add_f32_e32 v10, v146, v10
	v_add_f32_e32 v11, v147, v11
	v_add_f32_e32 v10, v148, v10
	v_add_f32_e32 v11, v149, v11
	v_add_f32_e32 v10, v154, v10
	v_add_f32_e32 v11, v155, v11
	v_add_f32_e32 v10, v156, v10
	v_add_f32_e32 v11, v157, v11
	v_add_f32_e32 v10, v10, v11
	v_cmp_nge_f32_e32 vcc, s58, v10
	s_cbranch_vccnz .Lfix_slow_4
	v_add_f32_e32 v224, v181, v10
	ds_read_b64_tr_b16 v[12:13], v213 offset:43008
	ds_read_b64_tr_b16 v[10:11], v207 offset:40960
	ds_read_b64_tr_b16 v[146:147], v207 offset:41472
	ds_read_b64_tr_b16 v[150:151], v207 offset:41984
	ds_read_b64_tr_b16 v[154:155], v207 offset:42496
	ds_read_b64_tr_b16 v[148:149], v213 offset:43520
	ds_read_b64_tr_b16 v[152:153], v213 offset:44032
	ds_read_b64_tr_b16 v[156:157], v213 offset:44544
	ds_read_b64_tr_b16 v[160:161], v213 offset:47104
	ds_read_b64_tr_b16 v[158:159], v207 offset:45056
	ds_read_b64_tr_b16 v[162:163], v207 offset:45568
	ds_read_b64_tr_b16 v[166:167], v207 offset:46080
	ds_read_b64_tr_b16 v[170:171], v207 offset:46592
	ds_read_b64_tr_b16 v[164:165], v213 offset:47616
	ds_read_b64_tr_b16 v[168:169], v213 offset:48128
	s_waitcnt lgkmcnt(7)
	v_mfma_f32_32x32x16_bf16 v[130:145], v[6:9], v[10:13], v[130:145]
	v_mfma_f32_32x32x16_bf16 v[114:129], v[6:9], v[146:149], v[114:129]
	v_mfma_f32_32x32x16_bf16 v[98:113], v[6:9], v[150:153], v[98:113]
	v_mfma_f32_32x32x16_bf16 v[18:33], v[6:9], v[154:157], v[18:33]
	ds_read_b64_tr_b16 v[172:173], v213 offset:48640
	s_waitcnt lgkmcnt(0)
	v_mfma_f32_32x32x16_bf16 v[130:145], v[2:5], v[158:161], v[130:145]
	v_mfma_f32_32x32x16_bf16 v[114:129], v[2:5], v[162:165], v[114:129]
	v_mfma_f32_32x32x16_bf16 v[98:113], v[2:5], v[166:169], v[98:113]
	v_mfma_f32_32x32x16_bf16 v[18:33], v[2:5], v[170:173], v[18:33]
	s_add_i32 s80, s80, 64
	s_add_u32 s94, s94, 0x20000
	s_addc_u32 s95, s95, 0
	s_waitcnt vmcnt(0)
	s_add_u32 s92, s92, 0x20000
	s_addc_u32 s93, s93, 0
	s_cmp_eq_u32 s76, s79
	v_subrev_u32_e32 v214, 64, v214
	s_barrier
	s_cbranch_scc1 .LBB0_352
.Lhead_p1:
	s_add_i32 s79, s79, 1
	s_mov_b32 m0, s77
	s_cmp_ge_u32 s79, s76
	s_cbranch_scc1 .Lq_prefetch_p1
	global_load_lds_dwordx4 v198, s[92:93]
.Ltile_p1:
	s_cmp_gt_i32 s80, 31
	s_cbranch_scc1 .Ldma_skip
	s_mov_b32 s81, 0x4000

; #define ATT_STAGE(t, buf) do { _Pragma("unroll") for (int i_ = 0; i_ < 2; ++i_) { \
;         glds16(Kt + (size_t)(t) * 131072, ksrc[i_], (unsigned)__builtin_amdgcn_readfirstlane(ldsb + KBUF + (buf) * 16384 + (w * 2 + i_) * 1024)); \
;         glds16(Vt + (size_t)(t) * 131072, vsrc[i_], (unsigned)__builtin_amdgcn_readfirstlane(ldsb + VBUF + (buf) * 16384 + (w * 2 + i_) * 1024)); } } while (0)
; __device__ __forceinline__ void attn_unit(ATT_LAS unsigned char* lds, const bf16_t* Qg, const bf16_t* Kg, const bf16_t* Vg, bf16_t* Og, int b, int head, int qb, float lam, const float* subg) {
;     ...
;         if (t + 1 < NT) ATT_STAGE(t + 1, buf ^ 1);
.LBB0_296_p1:
	s_add_i32 m0, s77, 0x8000
	s_cmp_ge_u32 s79, s76
	s_cbranch_scc1 .Ldma_s1_p1
	global_load_lds_dwordx4 v199, s[94:95]

; #define ATT_STAGE(t, buf) do { _Pragma("unroll") for (int i_ = 0; i_ < 2; ++i_) { \
;         glds16(Kt + (size_t)(t) * 131072, ksrc[i_], (unsigned)__builtin_amdgcn_readfirstlane(ldsb + KBUF + (buf) * 16384 + (w * 2 + i_) * 1024)); \
;         glds16(Vt + (size_t)(t) * 131072, vsrc[i_], (unsigned)__builtin_amdgcn_readfirstlane(ldsb + VBUF + (buf) * 16384 + (w * 2 + i_) * 1024)); } } while (0)
; __device__ __forceinline__ void attn_unit(ATT_LAS unsigned char* lds, const bf16_t* Qg, const bf16_t* Kg, const bf16_t* Vg, bf16_t* Og, int b, int head, int qb, float lam, const float* subg) {
;     ...
;         if (t + 1 < NT) ATT_STAGE(t + 1, buf ^ 1);
.Lns_311_p1:
	s_mov_b32 m0, s50
	s_cmp_ge_u32 s79, s76
	s_cbranch_scc1 .Ldma_ns2_p1
	global_load_lds_dwordx4 v200, s[92:93]

; #define ATT_STAGE(t, buf) do { _Pragma("unroll") for (int i_ = 0; i_ < 2; ++i_) { \
;         glds16(Kt + (size_t)(t) * 131072, ksrc[i_], (unsigned)__builtin_amdgcn_readfirstlane(ldsb + KBUF + (buf) * 16384 + (w * 2 + i_) * 1024)); \
;         glds16(Vt + (size_t)(t) * 131072, vsrc[i_], (unsigned)__builtin_amdgcn_readfirstlane(ldsb + VBUF + (buf) * 16384 + (w * 2 + i_) * 1024)); } } while (0)
; __device__ __forceinline__ void attn_unit(ATT_LAS unsigned char* lds, const bf16_t* Qg, const bf16_t* Kg, const bf16_t* Vg, bf16_t* Og, int b, int head, int qb, float lam, const float* subg) {
;     ...
;         if (t + 1 < NT) ATT_STAGE(t + 1, buf ^ 1);
.Lns_326_p1:
	s_add_i32 m0, s50, 0x8000
	s_cmp_ge_u32 s79, s76
	s_cbranch_scc1 .Ldma_ns3_p1
	global_load_lds_dwordx4 v201, s[94:95]

; __device__ __forceinline__ void apply_mask(bool MASK, f32x16& s0, int kvr, int r, int h) {
;     if (MASK) {
;         asm volatile("" ::: "memory");
;         const int d = r - 4 * h - kvr;
; #pragma unroll
;         for (int i = 0; i < 16; ++i) { if (((i & 3) + 8 * (i >> 2)) > d) s0[i] = -INFINITY; }
;     }
; }
; __device__ __forceinline__ void tile_body(bool MASK, const ATT_LAS unsigned char* kb, const ATT_LAS unsigned char* vb, const ATT_LAS unsigned char* qbase, const int (&kaddr)[4], const int (&vaddr)[2], ...
;     ...
;     apply_mask(MASK, Sb, kvrel, r, h); ls = l2;
;     sm = step_fused<true, true, false>(Sb, m2, l2, pkB, O1, pkA, vb, vaddr, Sa, kb + 8192, qbase, kaddr);
;     if (__any(!(sm <= GUARD))) slow_step<true>(MASK, Sb, kb, qbase, kaddr, vaddr, O2, m2, l2, ls, kvrel, r, h, wsf, pkB);
;     apply_mask(MASK, Sa, kvrel + 32, r, h); ls = l1;
;     sm = step_fused<true, true, true>(Sa, m1, l1, pkA, O2, pkB, vb, vaddr, Sb, kb + 8192, qbase, kaddr);
;     if (__any(!(sm <= GUARD))) slow_step<false>(MASK, Sa, kb + 8192, qbase, kaddr, vaddr, O1, m1, l1, ls, kvrel + 32, r, h, wsf, pkA);
;     apply_mask(MASK, Sb, kvrel + 32, r, h); ls = l2;
.Lns_338_p0:
	v_subrev_u32_e32 v6, 32, v214
	v_cmp_gt_i32_e64 s[34:35], 25, v6
	v_cmp_gt_i32_e64 s[36:37], 26, v6
	v_cmp_gt_i32_e64 s[28:29], 24, v6
	s_and_b64 s[34:35], s[36:37], s[34:35]
	v_cmp_gt_i32_e64 s[26:27], 19, v6
	s_and_b64 s[28:29], s[34:35], s[28:29]
	v_cmp_gt_i32_e64 s[24:25], 18, v6
	s_and_b64 s[26:27], s[28:29], s[26:27]
	v_cmp_gt_i32_e64 s[22:23], 17, v6
	s_and_b64 s[24:25], s[26:27], s[24:25]
	v_cmp_gt_i32_e64 s[20:21], 16, v6
	s_and_b64 s[22:23], s[24:25], s[22:23]
	v_cmp_gt_i32_e64 s[18:19], 11, v6
	s_and_b64 s[20:21], s[22:23], s[20:21]
	v_cmp_gt_i32_e64 s[16:17], 10, v6
	s_and_b64 s[18:19], s[20:21], s[18:19]
	v_cmp_gt_i32_e64 s[14:15], 9, v6
	s_and_b64 s[16:17], s[18:19], s[16:17]
	v_cmp_gt_i32_e64 s[12:13], 8, v6
	s_and_b64 s[14:15], s[16:17], s[14:15]
	v_cmp_gt_i32_e64 s[10:11], 3, v6
	s_and_b64 s[12:13], s[14:15], s[12:13]
	v_cmp_gt_i32_e64 s[8:9], 2, v6
	s_and_b64 s[10:11], s[12:13], s[10:11]
	v_cmp_gt_i32_e64 s[6:7], 1, v6
	s_and_b64 s[8:9], s[10:11], s[8:9]
	v_cmp_gt_i32_e32 vcc, 0, v6
	s_and_b64 s[6:7], s[8:9], s[6:7]
	s_and_b64 vcc, s[6:7], vcc
	v_cndmask_b32_e64 v176, v176, v17, s[36:37]
	v_cndmask_b32_e64 v175, v175, v17, s[34:35]
	v_cndmask_b32_e64 v174, v174, v17, s[28:29]
	v_cndmask_b32_e64 v173, v173, v17, s[26:27]
	v_cndmask_b32_e64 v172, v172, v17, s[24:25]
	v_cndmask_b32_e64 v171, v171, v17, s[22:23]
	v_cndmask_b32_e64 v170, v170, v17, s[20:21]
	v_cndmask_b32_e64 v169, v169, v17, s[18:19]
	v_cndmask_b32_e64 v168, v168, v17, s[16:17]
	v_cndmask_b32_e64 v167, v167, v17, s[14:15]
	v_cndmask_b32_e64 v166, v166, v17, s[12:13]
	v_cndmask_b32_e64 v165, v165, v17, s[10:11]
	v_cndmask_b32_e64 v164, v164, v17, s[8:9]
	v_cndmask_b32_e64 v163, v163, v17, s[6:7]
	v_cndmask_b32_e32 v162, v162, v17, vcc
	v_cmp_gt_i32_e32 vcc, 27, v6
	s_and_saveexec_b64 s[6:7], vcc
	v_mov_b32_e32 v177, s31
	s_or_b64 exec, exec, s[6:7]
	s_branch .Lns_341_p0
.Lns_308_p1:
	v_cmp_gt_i32_e64 s[34:35], 25, v214
	v_cmp_gt_i32_e64 s[36:37], 26, v214
	v_cmp_gt_i32_e64 s[28:29], 24, v214
	s_and_b64 s[34:35], s[36:37], s[34:35]
	v_cmp_gt_i32_e64 s[26:27], 19, v214
	s_and_b64 s[28:29], s[34:35], s[28:29]
	v_cmp_gt_i32_e64 s[24:25], 18, v214
	s_and_b64 s[26:27], s[28:29], s[26:27]
	v_cmp_gt_i32_e64 s[22:23], 17, v214
	s_and_b64 s[24:25], s[26:27], s[24:25]
	v_cmp_gt_i32_e64 s[20:21], 16, v214
	s_and_b64 s[22:23], s[24:25], s[22:23]
	v_cmp_gt_i32_e64 s[18:19], 11, v214
	s_and_b64 s[20:21], s[22:23], s[20:21]
	v_cmp_gt_i32_e64 s[16:17], 10, v214
	s_and_b64 s[18:19], s[20:21], s[18:19]
	v_cmp_gt_i32_e64 s[14:15], 9, v214
	s_and_b64 s[16:17], s[18:19], s[16:17]
	v_cmp_gt_i32_e64 s[12:13], 8, v214
	s_and_b64 s[14:15], s[16:17], s[14:15]
	v_cmp_gt_i32_e64 s[10:11], 3, v214
	s_and_b64 s[12:13], s[14:15], s[12:13]
	v_cmp_gt_i32_e64 s[8:9], 2, v214
	s_and_b64 s[10:11], s[12:13], s[10:11]
	v_cmp_gt_i32_e64 s[6:7], 1, v214
	s_and_b64 s[8:9], s[10:11], s[8:9]
	v_cmp_gt_i32_e32 vcc, 0, v214
	s_and_b64 s[6:7], s[8:9], s[6:7]
	s_and_b64 vcc, s[6:7], vcc
	v_cndmask_b32_e64 v172, v172, v17, s[36:37]
	v_cndmask_b32_e64 v171, v171, v17, s[34:35]
	v_cndmask_b32_e64 v170, v170, v17, s[28:29]
	v_cndmask_b32_e64 v169, v169, v17, s[26:27]
	v_cndmask_b32_e64 v168, v168, v17, s[24:25]
	v_cndmask_b32_e64 v167, v167, v17, s[22:23]
	v_cndmask_b32_e64 v166, v166, v17, s[20:21]
	v_cndmask_b32_e64 v165, v165, v17, s[18:19]
	v_cndmask_b32_e64 v164, v164, v17, s[16:17]
	v_cndmask_b32_e64 v163, v163, v17, s[14:15]
	v_cndmask_b32_e64 v162, v162, v17, s[12:13]
	v_cndmask_b32_e64 v161, v161, v17, s[10:11]
	v_cndmask_b32_e64 v160, v160, v17, s[8:9]
	v_cndmask_b32_e64 v159, v159, v17, s[6:7]
	v_cndmask_b32_e32 v158, v158, v17, vcc
	v_cmp_gt_i32_e32 vcc, 27, v214
	s_and_saveexec_b64 s[6:7], vcc
	v_mov_b32_e32 v173, s31
	s_or_b64 exec, exec, s[6:7]
	s_branch .Lns_311_p1

; __device__ __forceinline__ void apply_mask(bool MASK, f32x16& s0, int kvr, int r, int h) {
;     if (MASK) {
;         asm volatile("" ::: "memory");
;         const int d = r - 4 * h - kvr;
; #pragma unroll
;         for (int i = 0; i < 16; ++i) { if (((i & 3) + 8 * (i >> 2)) > d) s0[i] = -INFINITY; }
;     }
; }
.Lns_338_p1:
	v_subrev_u32_e32 v6, 32, v214
	v_cmp_gt_i32_e64 s[34:35], 25, v6
	v_cmp_gt_i32_e64 s[36:37], 26, v6
	v_cmp_gt_i32_e64 s[28:29], 24, v6
	s_and_b64 s[34:35], s[36:37], s[34:35]
	v_cmp_gt_i32_e64 s[26:27], 19, v6
	s_and_b64 s[28:29], s[34:35], s[28:29]
	v_cmp_gt_i32_e64 s[24:25], 18, v6
	s_and_b64 s[26:27], s[28:29], s[26:27]
	v_cmp_gt_i32_e64 s[22:23], 17, v6
	s_and_b64 s[24:25], s[26:27], s[24:25]
	v_cmp_gt_i32_e64 s[20:21], 16, v6
	s_and_b64 s[22:23], s[24:25], s[22:23]
	v_cmp_gt_i32_e64 s[18:19], 11, v6
	s_and_b64 s[20:21], s[22:23], s[20:21]
	v_cmp_gt_i32_e64 s[16:17], 10, v6
	s_and_b64 s[18:19], s[20:21], s[18:19]
	v_cmp_gt_i32_e64 s[14:15], 9, v6
	s_and_b64 s[16:17], s[18:19], s[16:17]
	v_cmp_gt_i32_e64 s[12:13], 8, v6
	s_and_b64 s[14:15], s[16:17], s[14:15]
	v_cmp_gt_i32_e64 s[10:11], 3, v6
	s_and_b64 s[12:13], s[14:15], s[12:13]
	v_cmp_gt_i32_e64 s[8:9], 2, v6
	s_and_b64 s[10:11], s[12:13], s[10:11]
	v_cmp_gt_i32_e64 s[6:7], 1, v6
	s_and_b64 s[8:9], s[10:11], s[8:9]
	v_cmp_gt_i32_e32 vcc, 0, v6
	s_and_b64 s[6:7], s[8:9], s[6:7]
	s_and_b64 vcc, s[6:7], vcc
	v_cndmask_b32_e64 v176, v176, v17, s[36:37]
	v_cndmask_b32_e64 v175, v175, v17, s[34:35]
	v_cndmask_b32_e64 v174, v174, v17, s[28:29]
	v_cndmask_b32_e64 v173, v173, v17, s[26:27]
	v_cndmask_b32_e64 v172, v172, v17, s[24:25]
	v_cndmask_b32_e64 v171, v171, v17, s[22:23]
	v_cndmask_b32_e64 v170, v170, v17, s[20:21]
	v_cndmask_b32_e64 v169, v169, v17, s[18:19]
	v_cndmask_b32_e64 v168, v168, v17, s[16:17]
	v_cndmask_b32_e64 v167, v167, v17, s[14:15]
	v_cndmask_b32_e64 v166, v166, v17, s[12:13]
	v_cndmask_b32_e64 v165, v165, v17, s[10:11]
	v_cndmask_b32_e64 v164, v164, v17, s[8:9]
	v_cndmask_b32_e64 v163, v163, v17, s[6:7]
	v_cndmask_b32_e32 v162, v162, v17, vcc
	v_cmp_gt_i32_e32 vcc, 27, v6
	s_and_saveexec_b64 s[6:7], vcc
	v_mov_b32_e32 v177, s31
	s_or_b64 exec, exec, s[6:7]
	s_branch .Lns_341_p1
.Lq_prefetch_p0:
	s_cmp_eq_u64 s[88:89], 0
	s_cbranch_scc0 .Lqp_cross_p0
	s_or_b32 s5, s68, s0
	s_mov_b32 s8, s42
	s_mov_b64 vcc, s[64:65]
	s_bitcmp1_b32 s77, 13
	s_cselect_b32 vcc_lo, s66, vcc_lo
	s_cselect_b32 vcc_hi, s67, vcc_hi
	s_branch .Lqp_go_p0

; __device__ __forceinline__ void attn_unit(ATT_LAS unsigned char* lds, const bf16_t* Qg, const bf16_t* Kg, const bf16_t* Vg, bf16_t* Og, int b, int head, int qb, float lam, const float* subg) {
;     ...
;     { const char* Qw = (const char*)(Qg + (rowbase + q0 + wq * 32) * PITCH + head * 128);
; #pragma unroll
;       for (int i = 0; i < 8; ++i) { const int row = 4 * i + (lane >> 4), pc = lane & 15;
;           glds16(Qw, (unsigned)(row * 2048 + ((pc ^ (row & 15)) << 4)), (unsigned)__builtin_amdgcn_readfirstlane(ldsb + QBUF + w * 8192 + i * 1024)); } }
.Lqp_go_p0:
	s_lshl_b32 s5, s5, 11
	s_add_u32 s6, s48, s5
	s_addc_u32 s7, s49, 0
	s_add_u32 s6, s6, s8
	s_addc_u32 s7, s7, 0
	v_and_b32_e32 v2, 1, v190
	v_lshlrev_b32_e32 v2, 7, v2
	v_and_b32_e32 v3, -2, v190
	v_lshl_or_b32 v3, v3, 10, v2
	s_and_b32 s5, s79, 1
	s_lshl_b32 s5, s5, 14
	s_add_i32 m0, s5, s77
	s_nop 0
	global_load_lds_dword v3, s[6:7]
	s_bitcmp1_b32 s77, 12
	s_cbranch_scc1 .Ltile_p0
	v_and_b32_e32 v3, 0x7e, v190
	v_lshl_or_b32 v3, v3, 10, v2
	s_add_i32 m0, m0, 0x100
	s_nop 0
	global_load_lds_dword v3, vcc
	s_branch .Ltile_p0
.Lq_prefetch_p1:
	s_cmp_eq_u64 s[88:89], 0
	s_cbranch_scc0 .Lqp_cross_p1
	s_or_b32 s5, s68, s0
	s_mov_b32 s8, s42
	s_mov_b64 vcc, s[64:65]
	s_bitcmp1_b32 s77, 13
	s_cselect_b32 vcc_lo, s66, vcc_lo
	s_cselect_b32 vcc_hi, s67, vcc_hi
	s_branch .Lqp_go_p1

; #define ATT_LAS __attribute__((address_space(3)))
; template <bool C1> __device__ __forceinline__ void slow_step(bool MASK, f32x16& S, const ATT_LAS unsigned char* kb, const ATT_LAS unsigned char* qbase, const int (&kaddr)[4], const int (&vaddr)[2], ...
;     l = l_saved;
;     qk_issue<C1>(S, kb, qbase, kaddr);
;     rowmax_rescale(MASK, S, O, m, l, kvr, r, h, wsf);
;     f32x16 dummy;
;     step_fused<false, false, false>(S, m, l, pk, O, pk, kb, vaddr, dummy, kb, qbase, kaddr);
; }
; __device__ __forceinline__ void attn_unit(ATT_LAS unsigned char* lds, const bf16_t* Qg, const bf16_t* Kg, const bf16_t* Vg, bf16_t* Og, int b, int head, int qb, float lam, const float* subg) {
;     ...
;     { const char* Qw = (const char*)(Qg + (rowbase + q0 + wq * 32) * PITCH + head * 128);
; #pragma unroll
;       for (int i = 0; i < 8; ++i) { const int row = 4 * i + (lane >> 4), pc = lane & 15;
;           glds16(Qw, (unsigned)(row * 2048 + ((pc ^ (row & 15)) << 4)), (unsigned)__builtin_amdgcn_readfirstlane(ldsb + QBUF + w * 8192 + i * 1024)); } }
.Lqp_go_p1:
	s_lshl_b32 s5, s5, 11
	s_add_u32 s6, s48, s5
	s_addc_u32 s7, s49, 0
	s_add_u32 s6, s6, s8
	s_addc_u32 s7, s7, 0
	v_and_b32_e32 v2, 1, v190
	v_lshlrev_b32_e32 v2, 7, v2
	v_and_b32_e32 v3, -2, v190
	v_lshl_or_b32 v3, v3, 10, v2
	s_and_b32 s5, s79, 1
	s_lshl_b32 s5, s5, 14
	s_add_i32 m0, s5, s77
	s_nop 0
	global_load_lds_dword v3, s[6:7]
	s_bitcmp1_b32 s77, 12
	s_cbranch_scc1 .Ltile_p1
	v_and_b32_e32 v3, 0x7e, v190
	v_lshl_or_b32 v3, v3, 10, v2
	s_add_i32 m0, m0, 0x100
	s_nop 0
	global_load_lds_dword v3, vcc
	s_branch .Ltile_p1
.Lfix_slow_1:
	v_add_u32_e32 v216, s81, v203
	v_add_u32_e32 v218, s81, v204
	v_add_u32_e32 v220, s81, v205
	v_add_u32_e32 v222, s81, v206
	v_add_u32_e32 v248, s81, v209
	v_add_u32_e32 v249, s81, v210
	v_add_u32_e32 v250, s81, v211
	v_add_u32_e32 v251, s81, v212
	s_branch .Lslow_1
